# one static s_setprio 1 for waves 4-7 during the recurrence phases 6a and 6c (reset at phase end); on top of previous best
# baseline (speedup 1.0000x reference)
; __global__ void __launch_bounds__(512, 2) fwd_megakernel(Params P) {
;     ...
;         const int wid = threadIdx.x >> 6, gw = wg * 8 + wid, ngw = nwg * 8;
;         float* lw = (float*)(smem + wid * WAVE_LDS);
;         for (int j = gw; j < 2048; j += ngw) gdn_job<0>(P, lw, ((j >> 9) << 1) | ((j >> 2) & 1), j & 3, (j >> 3) & 63);
.LBB0_481:
	s_or_b64 exec, exec, s[6:7]
	s_movk_i32 s6, 0x3000
	v_mad_i32_i24 v136, v189, s6, 0
	s_movk_i32 s6, 0x800
	s_lshl_b32 s42, s28, 3
	v_mul_i32_i24_e32 v133, 0x3000, v189
	v_cmp_gt_i32_e64 s[8:9], s6, v162
	v_bfe_u32 v111, v158, 3, 3
	v_lshrrev_b32_e32 v137, 1, v158
	s_waitcnt lgkmcnt(0)
	s_barrier
	s_cselect_b32 s101, 1, 0
	v_readfirstlane_b32 s100, v189
	s_cmp_ge_u32 s100, 4
	s_cbranch_scc0 .Lprio_done0
	s_setprio 1
.Lprio_done0:
	s_cmp_lg_u32 s101, 0
	s_and_saveexec_b64 s[10:11], s[8:9]
	s_cbranch_execz .LBB0_532
	s_add_u32 s12, s26, 0x4000000
	s_addc_u32 s13, s27, 0
	s_add_u32 s14, s26, 0x4080000
	v_and_b32_e32 v106, 0x70, v164
	s_addc_u32 s15, s27, 0
	v_mov_b32_e32 v113, 0
	v_lshl_add_u32 v139, v106, 2, v136
	s_add_u32 s18, s24, 0x4000000
	v_lshlrev_b32_e32 v112, 1, v106
	v_add_u32_e32 v2, 0, v133
	v_and_b32_e32 v138, 28, v137
	v_or_b32_e32 v107, 4, v106
	v_or_b32_e32 v118, 8, v106
	v_or_b32_e32 v119, 12, v106
	v_cmp_gt_u32_e32 vcc, 8, v160
	v_lshl_add_u32 v140, v111, 9, v139
	v_lshl_add_u32 v141, v160, 2, v136
	s_addc_u32 s19, s25, 0
	v_lshl_add_u64 v[108:109], s[26:27], 0, v[112:113]
	v_add_u32_e32 v142, 0x2400, v2
	s_mov_b64 s[56:57], 0
	v_lshlrev_b32_e32 v114, 1, v106
	v_mov_b32_e32 v115, v113
	s_movk_i32 s40, 0x60
	s_movk_i32 s41, 0x7ff
	v_mov_b32_e32 v120, v162
	s_branch .LBB0_484

; __device__ __forceinline__ void xcd_barrier(const XcdBarrier& b) {
;     asm volatile("s_waitcnt vmcnt(0)" ::: "memory");
;     __syncthreads();
;     if (threadIdx.x == 0) {
;         unsigned* bar = b.bar;
;         __builtin_amdgcn_s_waitcnt(0);
;         unsigned nloc = b.st[0], nx = b.st[1];
;         if (nloc == 0u) { xcd_barrier_complete(bar, b.x, nloc, nx); b.st[0] = nloc; b.st[1] = nx; }
; __global__ void __launch_bounds__(512, 2) fwd_megakernel(Params P) {
;     ...
;     xcd_barrier(xb);
.LBB0_532:
	s_or_b64 exec, exec, s[10:11]
	s_waitcnt vmcnt(0)
	s_setprio 0
	s_barrier
	s_and_saveexec_b64 s[6:7], s[20:21]
	s_cbranch_execz .LBB0_584
	s_add_i32 s10, 0, 0x20000
	v_mov_b32_e32 v2, s10
	s_waitcnt vmcnt(0) expcnt(0) lgkmcnt(0)
	ds_read_b32 v4, v2
	s_add_i32 s10, 0, 0x20004
	v_mov_b32_e32 v2, s10
	ds_read_b32 v2, v2
	s_waitcnt lgkmcnt(1)
	v_cmp_ne_u32_e32 vcc, 0, v4
	s_cbranch_vccnz .LBB0_548
	s_add_u32 s10, s26, 0x23c00200
	s_addc_u32 s11, s27, 0
	s_add_u32 s12, s26, 0x23c00400
	s_addc_u32 s13, s27, 0
	s_add_u32 s14, s26, 0x23c00500
	s_addc_u32 s15, s27, 0
	s_add_u32 s18, s26, 0x23c00600
	s_addc_u32 s19, s27, 0
	s_add_u32 s56, s26, 0x23c00700
	s_addc_u32 s57, s27, 0
	s_add_u32 s58, s26, 0x23c00800
	s_addc_u32 s59, s27, 0
	s_add_u32 s60, s26, 0x23c00900
	s_addc_u32 s61, s27, 0
	s_add_u32 s62, s26, 0x23c00a00
	s_addc_u32 s63, s27, 0
	s_add_u32 s64, s26, 0x23c00b00
	s_addc_u32 s65, s27, 0
	s_add_u32 s66, s26, 0x23c00c00
	s_addc_u32 s67, s27, 0
	s_add_u32 s68, s26, 0x23c00d00
	s_addc_u32 s69, s27, 0
	s_add_u32 s70, s26, 0x23c00e00
	s_addc_u32 s71, s27, 0
	s_add_u32 s72, s26, 0x23c00f00
	s_addc_u32 s73, s27, 0
	s_add_u32 s74, s26, 0x23c01000
	s_addc_u32 s75, s27, 0
	s_add_u32 s76, s26, 0x23c01100
	s_addc_u32 s77, s27, 0
	s_add_u32 s78, s26, 0x23c01200
	s_addc_u32 s79, s27, 0
	s_mul_i32 s40, s29, s94
	s_add_u32 s80, s26, 0x23c01300
	s_mul_i32 s40, s40, s28
	s_addc_u32 s81, s27, 0
	s_mov_b32 s41, 1
	v_mov_b32_e32 v18, 0
	s_branch .LBB0_536

; __global__ void __launch_bounds__(512, 2) fwd_megakernel(Params P) {
;     ...
;     {
;         const int wid = threadIdx.x >> 6, gw = wg * 8 + wid, ngw = nwg * 8;
;         float* lw = (float*)(smem + wid * WAVE_LDS);
;         for (int j = gw; j < 2048; j += ngw) gdn_job<2>(P, lw, ((j >> 9) << 1) | ((j >> 2) & 1), j & 3, (j >> 3) & 63);
.LBB0_654:
	s_or_b64 exec, exec, s[10:11]
	s_waitcnt lgkmcnt(0)
	s_barrier
	s_cselect_b32 s101, 1, 0
	v_readfirstlane_b32 s100, v189
	s_cmp_ge_u32 s100, 4
	s_cbranch_scc0 .Lprio_done1
	s_setprio 1
.Lprio_done1:
	s_cmp_lg_u32 s101, 0
	s_and_saveexec_b64 s[54:55], s[8:9]
	s_cbranch_execz .LBB0_689
	v_and_b32_e32 v4, 0x70, v164
	v_and_b32_e32 v6, 28, v42
	v_lshlrev_b32_e32 v5, 9, v111
	v_lshlrev_b32_e32 v7, 2, v4
	s_add_u32 s56, s26, 0x4000000
	v_lshlrev_b32_e32 v3, 7, v111
	v_add3_u32 v114, v136, v5, v7
	v_lshlrev_b32_e32 v5, 2, v6
	s_addc_u32 s57, s27, 0
	v_add3_u32 v115, v136, v3, v5
	v_and_b32_e32 v5, 0x70, v110
	s_add_u32 s58, s24, 0x6000000
	v_add_u32_e32 v5, 0, v5
	v_and_b32_e32 v112, 7, v158
	s_addc_u32 s59, s25, 0
	v_mov_b32_e32 v85, 0
	v_add_u32_e32 v116, 0x2000, v5
	v_lshlrev_b32_e32 v5, 5, v189
	v_lshlrev_b32_e32 v2, 4, v112
	s_add_u32 s60, s26, 0x4080000
	v_lshl_add_u32 v3, v160, 2, v136
	v_lshlrev_b32_e32 v82, 1, v112
	v_mov_b32_e32 v83, v85
	v_lshl_add_u32 v110, s2, 8, v5
	v_lshlrev_b32_e32 v90, 1, v4
	v_lshlrev_b32_e32 v94, 1, v6
	v_and_b32_e32 v113, 28, v137
	s_addc_u32 s61, s27, 0
	v_cmp_gt_u32_e64 s[18:19], 8, v160
	v_cmp_gt_u32_e64 s[8:9], 4, v112
	v_cmp_eq_u32_e64 s[10:11], 0, v112
	v_cmp_eq_u32_e64 s[12:13], 1, v112
	v_cmp_eq_u32_e64 s[14:15], 2, v112
	v_cmp_eq_u32_e64 s[16:17], 3, v112
	v_lshl_add_u32 v117, v112, 6, 0
	v_lshl_add_u64 v[86:87], s[26:27], 0, v[82:83]
	s_lshl_b32 s40, s28, 8
	s_mov_b64 s[62:63], 0
	v_lshlrev_b32_e32 v88, 2, v2
	v_mov_b32_e32 v89, v85
	v_mov_b32_e32 v92, v90
	v_mov_b32_e32 v93, v85
	v_mov_b32_e32 v96, v94
	v_mov_b32_e32 v97, v85
	s_movk_i32 s41, 0xff00
	s_mov_b32 s43, 0x340000
	s_add_i32 s70, 0, 0x2400
	s_mov_b64 s[64:65], 0x1a000
	s_movk_i32 s71, 0x7ff
	v_add_u32_e32 v118, 0x2400, v3
	v_mov_b32_e32 v119, v110
	v_mov_b32_e32 v120, v162
	s_branch .LBB0_657

; __device__ __forceinline__ void xcd_barrier(const XcdBarrier& b) {
;     asm volatile("s_waitcnt vmcnt(0)" ::: "memory");
;     __syncthreads();
;     if (threadIdx.x == 0) {
;         unsigned* bar = b.bar;
;         __builtin_amdgcn_s_waitcnt(0);
;         unsigned nloc = b.st[0], nx = b.st[1];
;         if (nloc == 0u) { xcd_barrier_complete(bar, b.x, nloc, nx); b.st[0] = nloc; b.st[1] = nx; }
; __global__ void __launch_bounds__(512, 2) fwd_megakernel(Params P) {
;     ...
;     xcd_barrier(xb);
.LBB0_689:
	s_or_b64 exec, exec, s[54:55]
	s_waitcnt vmcnt(0)
	s_setprio 0
	s_barrier
	s_and_saveexec_b64 s[8:9], s[20:21]
	s_cbranch_execz .LBB0_741
	s_add_i32 s10, 0, 0x20000
	v_mov_b32_e32 v2, s10
	s_waitcnt vmcnt(0) expcnt(0) lgkmcnt(0)
	ds_read_b32 v4, v2
	s_add_i32 s10, 0, 0x20004
	v_mov_b32_e32 v2, s10
	ds_read_b32 v2, v2
	s_waitcnt lgkmcnt(1)
	v_cmp_ne_u32_e32 vcc, 0, v4
	s_cbranch_vccnz .LBB0_705
	s_add_u32 s10, s26, 0x23c00200
	s_addc_u32 s11, s27, 0
	s_add_u32 s12, s26, 0x23c00400
	s_addc_u32 s13, s27, 0
	s_add_u32 s14, s26, 0x23c00500
	s_addc_u32 s15, s27, 0
	s_add_u32 s16, s26, 0x23c00600
	s_addc_u32 s17, s27, 0
	s_add_u32 s18, s26, 0x23c00700
	s_addc_u32 s19, s27, 0
	s_add_u32 s54, s26, 0x23c00800
	s_addc_u32 s55, s27, 0
	s_add_u32 s56, s26, 0x23c00900
	s_addc_u32 s57, s27, 0
	s_add_u32 s58, s26, 0x23c00a00
	s_addc_u32 s59, s27, 0
	s_add_u32 s60, s26, 0x23c00b00
	s_addc_u32 s61, s27, 0
	s_add_u32 s62, s26, 0x23c00c00
	s_addc_u32 s63, s27, 0
	s_add_u32 s64, s26, 0x23c00d00
	s_addc_u32 s65, s27, 0
	s_add_u32 s66, s26, 0x23c00e00
	s_addc_u32 s67, s27, 0
	s_add_u32 s68, s26, 0x23c00f00
	s_addc_u32 s69, s27, 0
	s_add_u32 s70, s26, 0x23c01000
	s_addc_u32 s71, s27, 0
	s_add_u32 s72, s26, 0x23c01100
	s_addc_u32 s73, s27, 0
	s_add_u32 s74, s26, 0x23c01200
	s_addc_u32 s75, s27, 0
	s_mul_i32 s40, s29, s94
	s_add_u32 s76, s26, 0x23c01300
	s_mul_i32 s40, s40, s28
	s_addc_u32 s77, s27, 0
	s_mov_b32 s41, 1
	v_mov_b32_e32 v18, 0
	s_branch .LBB0_693
